# expert-weight conversion tile stores inside P3 marked non-temporal (full 128-B lines, read only in P9/P10): less cache pollution beside attention/Hyena
# baseline (speedup 1.0000x reference)
.LBB0_657:
	v_lshl_add_u64 v[34:35], v[34:35], 1, s[86:87]
	v_lshl_add_u64 v[34:35], s[62:63], 1, v[34:35]
	v_lshlrev_b32_e32 v136, 1, v156
	s_waitcnt vmcnt(13)
	v_lshl_add_u64 v[38:39], v[34:35], 0, v[136:137]
	s_waitcnt vmcnt(12)
	v_cvt_pk_bf16_f32 v34, v2, v6
	s_waitcnt vmcnt(8)
	v_cvt_pk_bf16_f32 v35, v10, v14
	s_waitcnt vmcnt(4)
	v_cvt_pk_bf16_f32 v36, v18, v22
	s_waitcnt vmcnt(0)
	v_cvt_pk_bf16_f32 v37, v26, v30
	s_lshl_b64 s[10:11], s[96:97], 1
	global_store_dwordx4 v[38:39], v[34:37], off nt
	s_nop 1
	v_cvt_pk_bf16_f32 v34, v3, v7
	v_cvt_pk_bf16_f32 v35, v11, v15
	v_cvt_pk_bf16_f32 v36, v19, v23
	v_cvt_pk_bf16_f32 v37, v27, v31
	v_lshl_add_u64 v[2:3], v[38:39], 0, s[10:11]
	global_store_dwordx4 v[2:3], v[34:37], off nt
	v_lshl_add_u64 v[6:7], v[2:3], 0, s[10:11]
	v_cvt_pk_bf16_f32 v2, v5, v9
	v_cvt_pk_bf16_f32 v34, v4, v8
	v_cvt_pk_bf16_f32 v35, v12, v16
	v_cvt_pk_bf16_f32 v36, v20, v24
	v_cvt_pk_bf16_f32 v37, v28, v32
	global_store_dwordx4 v[6:7], v[34:37], off nt
	v_cvt_pk_bf16_f32 v3, v13, v17
	v_cvt_pk_bf16_f32 v4, v21, v25
	v_cvt_pk_bf16_f32 v5, v29, v33
	v_lshl_add_u64 v[6:7], v[6:7], 0, s[10:11]
	global_store_dwordx4 v[6:7], v[2:5], off nt

.LBB0_683:
	s_waitcnt vmcnt(14)
	v_add_u32_e32 v2, s62, v156
	v_mad_i64_i32 v[2:3], s[10:11], v2, s42, 0
	v_lshl_add_u64 v[2:3], v[2:3], 2, s[66:67]
	s_ashr_i32 s65, s64, 31
	s_ashr_i32 s43, s42, 31
	v_lshl_add_u64 v[2:3], s[64:65], 2, v[2:3]
	s_waitcnt vmcnt(1)
	v_lshlrev_b32_e32 v136, 2, v158
	v_lshl_add_u64 v[2:3], v[2:3], 0, v[136:137]
	s_lshl_b64 s[10:11], s[42:43], 2
	v_lshl_add_u64 v[6:7], v[2:3], 0, s[10:11]
	v_lshl_add_u64 v[10:11], v[6:7], 0, s[10:11]
	v_lshl_add_u64 v[14:15], v[10:11], 0, s[10:11]
	v_lshl_add_u64 v[18:19], v[14:15], 0, s[10:11]
	v_lshl_add_u64 v[22:23], v[18:19], 0, s[10:11]
	v_lshl_add_u64 v[26:27], v[22:23], 0, s[10:11]
	s_waitcnt vmcnt(0)
	v_lshl_add_u64 v[30:31], v[26:27], 0, s[10:11]
	global_load_dwordx4 v[102:105], v[2:3], off nt
	global_load_dwordx4 v[70:73], v[2:3], off offset:128 nt
	global_load_dwordx4 v[106:109], v[6:7], off nt
	global_load_dwordx4 v[74:77], v[6:7], off offset:128 nt
	global_load_dwordx4 v[110:113], v[10:11], off nt
	global_load_dwordx4 v[78:81], v[10:11], off offset:128 nt
	global_load_dwordx4 v[114:117], v[14:15], off nt
	global_load_dwordx4 v[82:85], v[14:15], off offset:128 nt
	global_load_dwordx4 v[118:121], v[18:19], off nt
	global_load_dwordx4 v[86:89], v[18:19], off offset:128 nt
	global_load_dwordx4 v[122:125], v[22:23], off nt
	global_load_dwordx4 v[90:93], v[22:23], off offset:128 nt
	global_load_dwordx4 v[126:129], v[26:27], off nt
	global_load_dwordx4 v[94:97], v[26:27], off offset:128 nt
	global_load_dwordx4 v[130:133], v[30:31], off nt
	global_load_dwordx4 v[98:101], v[30:31], off offset:128 nt
	global_load_dwordx4 v[34:37], v[2:3], off offset:256 nt
	s_nop 0
	global_load_dwordx4 v[2:5], v[2:3], off offset:384 nt
	s_nop 0
	global_load_dwordx4 v[38:41], v[6:7], off offset:256 nt
	s_nop 0
	global_load_dwordx4 v[6:9], v[6:7], off offset:384 nt
	s_nop 0
	global_load_dwordx4 v[42:45], v[10:11], off offset:256 nt
	s_nop 0
	global_load_dwordx4 v[10:13], v[10:11], off offset:384 nt
	s_nop 0
	global_load_dwordx4 v[46:49], v[14:15], off offset:256 nt
	s_nop 0
	global_load_dwordx4 v[14:17], v[14:15], off offset:384 nt
	s_nop 0
	global_load_dwordx4 v[50:53], v[18:19], off offset:256 nt
	s_nop 0
	global_load_dwordx4 v[18:21], v[18:19], off offset:384 nt
	s_nop 0
	global_load_dwordx4 v[54:57], v[22:23], off offset:256 nt
	s_nop 0
	global_load_dwordx4 v[22:25], v[22:23], off offset:384 nt
	s_nop 0
	global_load_dwordx4 v[58:61], v[26:27], off offset:256 nt
	s_nop 0
	global_load_dwordx4 v[26:29], v[26:27], off offset:384 nt
	s_nop 0
	global_load_dwordx4 v[62:65], v[30:31], off offset:256 nt
	s_nop 0
	global_load_dwordx4 v[30:33], v[30:31], off offset:384 nt
	s_cmp_lg_u32 s18, 0
	s_cselect_b64 s[10:11], -1, 0
	s_ashr_i32 s97, s96, 31
	s_ashr_i32 s63, s62, 31
	v_add_u32_e32 v136, s17, v158
	s_cmp_eq_u32 s18, 0
	v_mad_i64_i32 v[198:199], s[34:35], v136, s96, 0
	s_cbranch_scc1 .LBB0_694
	s_waitcnt vmcnt(31)
	v_mul_f32_e32 v136, 0x42000000, v102
	s_waitcnt vmcnt(29)
	v_mul_f32_e32 v169, 0x42000000, v106
	v_mov_b32_e32 v202, v137
	v_cvt_pk_fp8_f32 v202, v136, v169
	s_waitcnt vmcnt(23)
	v_mul_f32_e32 v136, 0x42000000, v118
	s_waitcnt vmcnt(21)
	v_mul_f32_e32 v169, 0x42000000, v122
	v_mov_b32_e32 v203, v137
	v_cvt_pk_fp8_f32 v203, v136, v169
	v_mul_f32_e32 v171, 0x42000000, v110
	v_mul_f32_e32 v173, 0x42000000, v114
	v_cvt_pk_fp8_f32 v202, v171, v173 op_sel:[0,0,1]
	s_waitcnt vmcnt(19)
	v_mul_f32_e32 v171, 0x42000000, v126
	s_waitcnt vmcnt(17)
	v_mul_f32_e32 v173, 0x42000000, v130
	v_cvt_pk_fp8_f32 v203, v171, v173 op_sel:[0,0,1]
	v_lshl_add_u64 v[200:201], s[86:87], 0, v[198:199]
	v_lshl_add_u64 v[200:201], v[200:201], 0, s[62:63]
	v_lshl_add_u64 v[200:201], v[200:201], 0, v[156:157]
	global_store_dwordx2 v[200:201], v[202:203], off nt
	v_mul_f32_e32 v136, 0x42000000, v103
	v_mul_f32_e32 v169, 0x42000000, v107
	v_mov_b32_e32 v202, v137
	v_cvt_pk_fp8_f32 v202, v136, v169
	v_mul_f32_e32 v136, 0x42000000, v119
	v_mul_f32_e32 v169, 0x42000000, v123
	v_mov_b32_e32 v203, v137
	v_cvt_pk_fp8_f32 v203, v136, v169
	v_mul_f32_e32 v171, 0x42000000, v111
	v_mul_f32_e32 v173, 0x42000000, v115
	v_cvt_pk_fp8_f32 v202, v171, v173 op_sel:[0,0,1]
	v_mul_f32_e32 v171, 0x42000000, v127
	v_mul_f32_e32 v173, 0x42000000, v131
	v_cvt_pk_fp8_f32 v203, v171, v173 op_sel:[0,0,1]
	v_lshl_add_u64 v[200:201], v[200:201], 0, s[96:97]
	v_mul_f32_e32 v136, 0x42000000, v104
	v_mul_f32_e32 v169, 0x42000000, v108
	global_store_dwordx2 v[200:201], v[202:203], off nt
	v_mov_b32_e32 v202, v137
	v_cvt_pk_fp8_f32 v202, v136, v169
	v_mul_f32_e32 v136, 0x42000000, v120
	v_mul_f32_e32 v169, 0x42000000, v124
	v_mov_b32_e32 v203, v137
	v_cvt_pk_fp8_f32 v203, v136, v169
	v_mul_f32_e32 v171, 0x42000000, v112
	v_mul_f32_e32 v173, 0x42000000, v116
	v_cvt_pk_fp8_f32 v202, v171, v173 op_sel:[0,0,1]
	v_mul_f32_e32 v171, 0x42000000, v128
	v_mul_f32_e32 v173, 0x42000000, v132
	v_cvt_pk_fp8_f32 v203, v171, v173 op_sel:[0,0,1]
	v_lshl_add_u64 v[200:201], v[200:201], 0, s[96:97]
	v_mul_f32_e32 v136, 0x42000000, v105
	v_mul_f32_e32 v169, 0x42000000, v109
	global_store_dwordx2 v[200:201], v[202:203], off nt
	v_mov_b32_e32 v202, v137
	v_cvt_pk_fp8_f32 v202, v136, v169
	v_mul_f32_e32 v136, 0x42000000, v121
	v_mul_f32_e32 v169, 0x42000000, v125
	v_mov_b32_e32 v203, v137
	v_cvt_pk_fp8_f32 v203, v136, v169
	v_mul_f32_e32 v171, 0x42000000, v113
	v_mul_f32_e32 v173, 0x42000000, v117
	v_cvt_pk_fp8_f32 v202, v171, v173 op_sel:[0,0,1]
	v_mul_f32_e32 v171, 0x42000000, v129
	v_mul_f32_e32 v173, 0x42000000, v133
	v_cvt_pk_fp8_f32 v203, v171, v173 op_sel:[0,0,1]
	v_lshl_add_u64 v[200:201], v[200:201], 0, s[96:97]
	global_store_dwordx2 v[200:201], v[202:203], off nt
	s_cbranch_execnz .LBB0_686
.LBB0_685:
	v_lshl_add_u64 v[198:199], v[198:199], 1, s[86:87]
	v_lshl_add_u64 v[198:199], s[62:63], 1, v[198:199]
	v_lshlrev_b32_e32 v136, 1, v156
	v_lshl_add_u64 v[202:203], v[198:199], 0, v[136:137]
	s_waitcnt vmcnt(29)
	v_cvt_pk_bf16_f32 v198, v102, v106
	s_waitcnt vmcnt(25)
	v_cvt_pk_bf16_f32 v199, v110, v114
	s_waitcnt vmcnt(21)
	v_cvt_pk_bf16_f32 v200, v118, v122
	s_waitcnt vmcnt(17)
	v_cvt_pk_bf16_f32 v201, v126, v130
	s_lshl_b64 s[34:35], s[96:97], 1
	global_store_dwordx4 v[202:203], v[198:201], off nt
	s_nop 1
	v_cvt_pk_bf16_f32 v198, v103, v107
	v_cvt_pk_bf16_f32 v199, v111, v115
	v_cvt_pk_bf16_f32 v200, v119, v123
	v_cvt_pk_bf16_f32 v201, v127, v131
	v_lshl_add_u64 v[102:103], v[202:203], 0, s[34:35]
	global_store_dwordx4 v[102:103], v[198:201], off nt
	v_lshl_add_u64 v[106:107], v[102:103], 0, s[34:35]
	v_cvt_pk_bf16_f32 v102, v105, v109
	v_cvt_pk_bf16_f32 v198, v104, v108
	v_cvt_pk_bf16_f32 v199, v112, v116
	v_cvt_pk_bf16_f32 v200, v120, v124
	v_cvt_pk_bf16_f32 v201, v128, v132
	global_store_dwordx4 v[106:107], v[198:201], off nt
	v_cvt_pk_bf16_f32 v103, v113, v117
	v_cvt_pk_bf16_f32 v104, v121, v125
	v_cvt_pk_bf16_f32 v105, v129, v133
	v_lshl_add_u64 v[106:107], v[106:107], 0, s[34:35]
	global_store_dwordx4 v[106:107], v[102:105], off nt
.LBB0_686:
	s_waitcnt vmcnt(31)
	s_nop 0
	v_add_u32_e32 v102, s17, v145
	v_cndmask_b32_e64 v103, 0, 1, s[10:11]
	v_cmp_ne_u32_e64 s[34:35], 1, v103
	s_andn2_b64 vcc, exec, s[10:11]
	v_mad_i64_i32 v[102:103], s[10:11], v102, s96, 0
	s_cbranch_vccnz .LBB0_695
	s_waitcnt vmcnt(29)
	v_mul_f32_e32 v107, 0x42000000, v70
	s_waitcnt vmcnt(28)
	v_mul_f32_e32 v108, 0x42000000, v74
	v_mov_b32_e32 v106, v137
	v_cvt_pk_fp8_f32 v106, v107, v108
	s_waitcnt vmcnt(26)
	v_mul_f32_e32 v109, 0x42000000, v78
	s_waitcnt vmcnt(24)
	v_mul_f32_e32 v110, 0x42000000, v82
	s_waitcnt vmcnt(22)
	v_mul_f32_e32 v108, 0x42000000, v86
	v_cvt_pk_fp8_f32 v106, v109, v110 op_sel:[0,0,1]
	s_waitcnt vmcnt(20)
	v_mul_f32_e32 v109, 0x42000000, v90
	v_mov_b32_e32 v107, v137
	v_cvt_pk_fp8_f32 v107, v108, v109
	s_waitcnt vmcnt(18)
	v_mul_f32_e32 v110, 0x42000000, v94
	s_waitcnt vmcnt(16)
	v_mul_f32_e32 v111, 0x42000000, v98
	v_lshl_add_u64 v[104:105], s[86:87], 0, v[102:103]
	v_cvt_pk_fp8_f32 v107, v110, v111 op_sel:[0,0,1]
	v_lshl_add_u64 v[104:105], v[104:105], 0, s[62:63]
	v_lshl_add_u64 v[104:105], v[104:105], 0, v[156:157]
	v_mul_f32_e32 v108, 0x42000000, v75
	global_store_dwordx2 v[104:105], v[106:107], off nt
	v_mul_f32_e32 v107, 0x42000000, v71
	v_mov_b32_e32 v106, v137
	v_cvt_pk_fp8_f32 v106, v107, v108
	v_mul_f32_e32 v109, 0x42000000, v79
	v_mul_f32_e32 v110, 0x42000000, v83
	v_mul_f32_e32 v108, 0x42000000, v87
	v_cvt_pk_fp8_f32 v106, v109, v110 op_sel:[0,0,1]
	v_mul_f32_e32 v109, 0x42000000, v91
	v_mov_b32_e32 v107, v137
	v_cvt_pk_fp8_f32 v107, v108, v109
	v_mul_f32_e32 v110, 0x42000000, v95
	v_mul_f32_e32 v111, 0x42000000, v99
	v_lshl_add_u64 v[104:105], v[104:105], 0, s[96:97]
	v_cvt_pk_fp8_f32 v107, v110, v111 op_sel:[0,0,1]
	v_mul_f32_e32 v108, 0x42000000, v76
	v_mul_f32_e32 v109, 0x42000000, v80
	v_mul_f32_e32 v110, 0x42000000, v84
	global_store_dwordx2 v[104:105], v[106:107], off nt
	v_mul_f32_e32 v107, 0x42000000, v72
	v_mov_b32_e32 v106, v137
	v_cvt_pk_fp8_f32 v106, v107, v108
	v_mul_f32_e32 v108, 0x42000000, v88
	v_mov_b32_e32 v107, v137
	v_mul_f32_e32 v111, 0x42000000, v100
	v_cvt_pk_fp8_f32 v106, v109, v110 op_sel:[0,0,1]
	v_mul_f32_e32 v109, 0x42000000, v92
	v_cvt_pk_fp8_f32 v107, v108, v109
	v_mul_f32_e32 v110, 0x42000000, v96
	v_lshl_add_u64 v[104:105], v[104:105], 0, s[96:97]
	v_mul_f32_e32 v108, 0x42000000, v77
	v_cvt_pk_fp8_f32 v107, v110, v111 op_sel:[0,0,1]
	v_mul_f32_e32 v109, 0x42000000, v81
	v_mul_f32_e32 v110, 0x42000000, v85
	v_mul_f32_e32 v111, 0x42000000, v101
	global_store_dwordx2 v[104:105], v[106:107], off nt
	v_mul_f32_e32 v107, 0x42000000, v73
	v_mov_b32_e32 v106, v137
	v_cvt_pk_fp8_f32 v106, v107, v108
	v_mul_f32_e32 v108, 0x42000000, v89
	v_mov_b32_e32 v107, v137
	v_lshl_add_u64 v[104:105], v[104:105], 0, s[96:97]
	v_cvt_pk_fp8_f32 v106, v109, v110 op_sel:[0,0,1]
	v_mul_f32_e32 v109, 0x42000000, v93
	v_cvt_pk_fp8_f32 v107, v108, v109
	v_mul_f32_e32 v110, 0x42000000, v97
	v_cvt_pk_fp8_f32 v107, v110, v111 op_sel:[0,0,1]
	global_store_dwordx2 v[104:105], v[106:107], off nt
	s_cbranch_execnz .LBB0_689
.LBB0_688:
	v_lshl_add_u64 v[102:103], v[102:103], 1, s[86:87]
	v_lshl_add_u64 v[102:103], s[62:63], 1, v[102:103]
	v_lshlrev_b32_e32 v136, 1, v156
	s_waitcnt vmcnt(29)
	v_lshl_add_u64 v[106:107], v[102:103], 0, v[136:137]
	s_waitcnt vmcnt(28)
	v_cvt_pk_bf16_f32 v102, v70, v74
	s_waitcnt vmcnt(24)
	v_cvt_pk_bf16_f32 v103, v78, v82
	s_waitcnt vmcnt(20)
	v_cvt_pk_bf16_f32 v104, v86, v90
	s_waitcnt vmcnt(16)
	v_cvt_pk_bf16_f32 v105, v94, v98
	s_lshl_b64 s[10:11], s[96:97], 1
	global_store_dwordx4 v[106:107], v[102:105], off nt
	s_nop 1
	v_cvt_pk_bf16_f32 v102, v71, v75
	v_cvt_pk_bf16_f32 v103, v79, v83
	v_cvt_pk_bf16_f32 v104, v87, v91
	v_cvt_pk_bf16_f32 v105, v95, v99
	v_lshl_add_u64 v[70:71], v[106:107], 0, s[10:11]
	global_store_dwordx4 v[70:71], v[102:105], off nt
	v_lshl_add_u64 v[74:75], v[70:71], 0, s[10:11]
	v_cvt_pk_bf16_f32 v70, v73, v77
	v_cvt_pk_bf16_f32 v102, v72, v76
	v_cvt_pk_bf16_f32 v103, v80, v84
	v_cvt_pk_bf16_f32 v104, v88, v92
	v_cvt_pk_bf16_f32 v105, v96, v100
	global_store_dwordx4 v[74:75], v[102:105], off nt
	v_cvt_pk_bf16_f32 v71, v81, v85
	v_cvt_pk_bf16_f32 v72, v89, v93
	v_cvt_pk_bf16_f32 v73, v97, v101
	v_lshl_add_u64 v[74:75], v[74:75], 0, s[10:11]
	global_store_dwordx4 v[74:75], v[70:73], off nt
.LBB0_689:
	s_waitcnt vmcnt(30)
	s_nop 0
	v_add_u32_e32 v70, s17, v153
	s_and_b64 vcc, exec, s[34:35]
	v_mad_i64_i32 v[70:71], s[10:11], v70, s96, 0
	s_cbranch_vccnz .LBB0_696
	s_waitcnt vmcnt(15)
	v_mul_f32_e32 v75, 0x42000000, v34
	s_waitcnt vmcnt(13)
	v_mul_f32_e32 v76, 0x42000000, v38
	v_mov_b32_e32 v74, v137
	v_cvt_pk_fp8_f32 v74, v75, v76
	s_waitcnt vmcnt(11)
	v_mul_f32_e32 v77, 0x42000000, v42
	s_waitcnt vmcnt(9)
	v_mul_f32_e32 v78, 0x42000000, v46
	s_waitcnt vmcnt(7)
	v_mul_f32_e32 v76, 0x42000000, v50
	v_cvt_pk_fp8_f32 v74, v77, v78 op_sel:[0,0,1]
	s_waitcnt vmcnt(5)
	v_mul_f32_e32 v77, 0x42000000, v54
	v_mov_b32_e32 v75, v137
	v_cvt_pk_fp8_f32 v75, v76, v77
	s_waitcnt vmcnt(3)
	v_mul_f32_e32 v78, 0x42000000, v58
	s_waitcnt vmcnt(1)
	v_mul_f32_e32 v79, 0x42000000, v62
	v_lshl_add_u64 v[72:73], s[86:87], 0, v[70:71]
	v_cvt_pk_fp8_f32 v75, v78, v79 op_sel:[0,0,1]
	v_lshl_add_u64 v[72:73], v[72:73], 0, s[62:63]
	v_lshl_add_u64 v[72:73], v[72:73], 0, v[156:157]
	v_mul_f32_e32 v76, 0x42000000, v39
	global_store_dwordx2 v[72:73], v[74:75], off nt
	v_mul_f32_e32 v75, 0x42000000, v35
	v_mov_b32_e32 v74, v137
	v_cvt_pk_fp8_f32 v74, v75, v76
	v_mul_f32_e32 v77, 0x42000000, v43
	v_mul_f32_e32 v78, 0x42000000, v47
	v_mul_f32_e32 v76, 0x42000000, v51
	v_cvt_pk_fp8_f32 v74, v77, v78 op_sel:[0,0,1]
	v_mul_f32_e32 v77, 0x42000000, v55
	v_mov_b32_e32 v75, v137
	v_cvt_pk_fp8_f32 v75, v76, v77
	v_mul_f32_e32 v78, 0x42000000, v59
	v_mul_f32_e32 v79, 0x42000000, v63
	v_lshl_add_u64 v[72:73], v[72:73], 0, s[96:97]
	v_cvt_pk_fp8_f32 v75, v78, v79 op_sel:[0,0,1]
	v_mul_f32_e32 v76, 0x42000000, v40
	v_mul_f32_e32 v77, 0x42000000, v44
	v_mul_f32_e32 v78, 0x42000000, v48
	global_store_dwordx2 v[72:73], v[74:75], off nt
	v_mul_f32_e32 v75, 0x42000000, v36
	v_mov_b32_e32 v74, v137
	v_cvt_pk_fp8_f32 v74, v75, v76
	v_mul_f32_e32 v76, 0x42000000, v52
	v_mov_b32_e32 v75, v137
	v_mul_f32_e32 v79, 0x42000000, v64
	v_cvt_pk_fp8_f32 v74, v77, v78 op_sel:[0,0,1]
	v_mul_f32_e32 v77, 0x42000000, v56
	v_cvt_pk_fp8_f32 v75, v76, v77
	v_mul_f32_e32 v78, 0x42000000, v60
	v_lshl_add_u64 v[72:73], v[72:73], 0, s[96:97]
	v_mul_f32_e32 v76, 0x42000000, v41
	v_cvt_pk_fp8_f32 v75, v78, v79 op_sel:[0,0,1]
	v_mul_f32_e32 v77, 0x42000000, v45
	v_mul_f32_e32 v78, 0x42000000, v49
	v_mul_f32_e32 v79, 0x42000000, v65
	global_store_dwordx2 v[72:73], v[74:75], off nt
	v_mul_f32_e32 v75, 0x42000000, v37
	v_mov_b32_e32 v74, v137
	v_cvt_pk_fp8_f32 v74, v75, v76
	v_mul_f32_e32 v76, 0x42000000, v53
	v_mov_b32_e32 v75, v137
	v_lshl_add_u64 v[72:73], v[72:73], 0, s[96:97]
	v_cvt_pk_fp8_f32 v74, v77, v78 op_sel:[0,0,1]
	v_mul_f32_e32 v77, 0x42000000, v57
	v_cvt_pk_fp8_f32 v75, v76, v77
	v_mul_f32_e32 v78, 0x42000000, v61
	v_cvt_pk_fp8_f32 v75, v78, v79 op_sel:[0,0,1]
	global_store_dwordx2 v[72:73], v[74:75], off nt
	s_cbranch_execnz .LBB0_692
.LBB0_691:
	v_lshl_add_u64 v[70:71], v[70:71], 1, s[86:87]
	v_lshl_add_u64 v[70:71], s[62:63], 1, v[70:71]
	v_lshlrev_b32_e32 v136, 1, v156
	s_waitcnt vmcnt(28)
	v_lshl_add_u64 v[74:75], v[70:71], 0, v[136:137]
	s_waitcnt vmcnt(13)
	v_cvt_pk_bf16_f32 v70, v34, v38
	s_waitcnt vmcnt(9)
	v_cvt_pk_bf16_f32 v71, v42, v46
	s_waitcnt vmcnt(5)
	v_cvt_pk_bf16_f32 v72, v50, v54
	s_waitcnt vmcnt(1)
	v_cvt_pk_bf16_f32 v73, v58, v62
	s_lshl_b64 s[10:11], s[96:97], 1
	global_store_dwordx4 v[74:75], v[70:73], off nt
	s_nop 1
	v_cvt_pk_bf16_f32 v70, v35, v39
	v_cvt_pk_bf16_f32 v71, v43, v47
	v_cvt_pk_bf16_f32 v72, v51, v55
	v_cvt_pk_bf16_f32 v73, v59, v63
	v_lshl_add_u64 v[34:35], v[74:75], 0, s[10:11]
	global_store_dwordx4 v[34:35], v[70:73], off nt
	v_lshl_add_u64 v[38:39], v[34:35], 0, s[10:11]
	v_cvt_pk_bf16_f32 v34, v37, v41
	v_cvt_pk_bf16_f32 v70, v36, v40
	v_cvt_pk_bf16_f32 v71, v44, v48
	v_cvt_pk_bf16_f32 v72, v52, v56
	v_cvt_pk_bf16_f32 v73, v60, v64
	global_store_dwordx4 v[38:39], v[70:73], off nt
	v_cvt_pk_bf16_f32 v35, v45, v49
	v_cvt_pk_bf16_f32 v36, v53, v57
	v_cvt_pk_bf16_f32 v37, v61, v65
	v_lshl_add_u64 v[38:39], v[38:39], 0, s[10:11]
	global_store_dwordx4 v[38:39], v[34:37], off nt
.LBB0_692:
	s_waitcnt vmcnt(15)
	s_nop 0
	v_add_u32_e32 v34, s17, v155
	s_and_b64 vcc, exec, s[34:35]
	v_mad_i64_i32 v[34:35], s[10:11], v34, s96, 0
	s_cbranch_vccnz .LBB0_697
	s_waitcnt vmcnt(13)
	v_mul_f32_e32 v39, 0x42000000, v2
	s_waitcnt vmcnt(12)
	v_mul_f32_e32 v40, 0x42000000, v6
	v_mov_b32_e32 v38, v137
	v_cvt_pk_fp8_f32 v38, v39, v40
	s_waitcnt vmcnt(10)
	v_mul_f32_e32 v41, 0x42000000, v10
	s_waitcnt vmcnt(8)
	v_mul_f32_e32 v42, 0x42000000, v14
	s_waitcnt vmcnt(6)
	v_mul_f32_e32 v40, 0x42000000, v18
	v_cvt_pk_fp8_f32 v38, v41, v42 op_sel:[0,0,1]
	s_waitcnt vmcnt(4)
	v_mul_f32_e32 v41, 0x42000000, v22
	v_mov_b32_e32 v39, v137
	v_cvt_pk_fp8_f32 v39, v40, v41
	s_waitcnt vmcnt(2)
	v_mul_f32_e32 v42, 0x42000000, v26
	s_waitcnt vmcnt(0)
	v_mul_f32_e32 v43, 0x42000000, v30
	v_lshl_add_u64 v[36:37], s[86:87], 0, v[34:35]
	v_cvt_pk_fp8_f32 v39, v42, v43 op_sel:[0,0,1]
	v_lshl_add_u64 v[36:37], v[36:37], 0, s[62:63]
	v_lshl_add_u64 v[36:37], v[36:37], 0, v[156:157]
	v_mul_f32_e32 v40, 0x42000000, v7
	global_store_dwordx2 v[36:37], v[38:39], off nt
	v_mul_f32_e32 v39, 0x42000000, v3
	v_mov_b32_e32 v38, v137
	v_cvt_pk_fp8_f32 v38, v39, v40
	v_mul_f32_e32 v41, 0x42000000, v11
	v_mul_f32_e32 v42, 0x42000000, v15
	v_mul_f32_e32 v40, 0x42000000, v19
	v_cvt_pk_fp8_f32 v38, v41, v42 op_sel:[0,0,1]
	v_mul_f32_e32 v41, 0x42000000, v23
	v_mov_b32_e32 v39, v137
	v_cvt_pk_fp8_f32 v39, v40, v41
	v_mul_f32_e32 v42, 0x42000000, v27
	v_mul_f32_e32 v43, 0x42000000, v31
	v_lshl_add_u64 v[36:37], v[36:37], 0, s[96:97]
	v_cvt_pk_fp8_f32 v39, v42, v43 op_sel:[0,0,1]
	v_mul_f32_e32 v40, 0x42000000, v8
	v_mul_f32_e32 v41, 0x42000000, v12
	v_mul_f32_e32 v42, 0x42000000, v16
	global_store_dwordx2 v[36:37], v[38:39], off nt
	v_mul_f32_e32 v39, 0x42000000, v4
	v_mov_b32_e32 v38, v137
	v_cvt_pk_fp8_f32 v38, v39, v40
	v_mul_f32_e32 v40, 0x42000000, v20
	v_mov_b32_e32 v39, v137
	v_mul_f32_e32 v43, 0x42000000, v32
	v_cvt_pk_fp8_f32 v38, v41, v42 op_sel:[0,0,1]
	v_mul_f32_e32 v41, 0x42000000, v24
	v_cvt_pk_fp8_f32 v39, v40, v41
	v_mul_f32_e32 v42, 0x42000000, v28
	v_lshl_add_u64 v[36:37], v[36:37], 0, s[96:97]
	v_mul_f32_e32 v40, 0x42000000, v9
	v_cvt_pk_fp8_f32 v39, v42, v43 op_sel:[0,0,1]
	v_mul_f32_e32 v41, 0x42000000, v13
	v_mul_f32_e32 v42, 0x42000000, v17
	v_mul_f32_e32 v43, 0x42000000, v33
	global_store_dwordx2 v[36:37], v[38:39], off nt
	v_mul_f32_e32 v39, 0x42000000, v5
	v_mov_b32_e32 v38, v137
	v_cvt_pk_fp8_f32 v38, v39, v40
	v_mul_f32_e32 v40, 0x42000000, v21
	v_mov_b32_e32 v39, v137
	v_lshl_add_u64 v[36:37], v[36:37], 0, s[96:97]
	v_cvt_pk_fp8_f32 v38, v41, v42 op_sel:[0,0,1]
	v_mul_f32_e32 v41, 0x42000000, v25
	v_cvt_pk_fp8_f32 v39, v40, v41
	v_mul_f32_e32 v42, 0x42000000, v29
	v_cvt_pk_fp8_f32 v39, v42, v43 op_sel:[0,0,1]
	global_store_dwordx2 v[36:37], v[38:39], off nt
	s_cbranch_execnz .LBB0_658
	s_branch .LBB0_657

.LBB0_712:
	v_lshl_add_u64 v[34:35], v[34:35], 1, s[86:87]
	v_lshl_add_u64 v[34:35], s[60:61], 1, v[34:35]
	s_waitcnt vmcnt(13)
	v_lshl_add_u64 v[38:39], v[34:35], 0, v[136:137]
	s_waitcnt vmcnt(12)
	v_cvt_pk_bf16_f32 v34, v2, v6
	s_waitcnt vmcnt(8)
	v_cvt_pk_bf16_f32 v35, v10, v14
	s_waitcnt vmcnt(4)
	v_cvt_pk_bf16_f32 v36, v18, v22
	s_waitcnt vmcnt(0)
	v_cvt_pk_bf16_f32 v37, v26, v30
	s_lshl_b64 s[10:11], s[66:67], 1
	global_store_dwordx4 v[38:39], v[34:37], off nt
	s_nop 1
	v_cvt_pk_bf16_f32 v34, v3, v7
	v_cvt_pk_bf16_f32 v35, v11, v15
	v_cvt_pk_bf16_f32 v36, v19, v23
	v_cvt_pk_bf16_f32 v37, v27, v31
	v_lshl_add_u64 v[2:3], v[38:39], 0, s[10:11]
	global_store_dwordx4 v[2:3], v[34:37], off nt
	v_lshl_add_u64 v[6:7], v[2:3], 0, s[10:11]
	v_cvt_pk_bf16_f32 v2, v5, v9
	v_cvt_pk_bf16_f32 v34, v4, v8
	v_cvt_pk_bf16_f32 v35, v12, v16
	v_cvt_pk_bf16_f32 v36, v20, v24
	v_cvt_pk_bf16_f32 v37, v28, v32
	global_store_dwordx4 v[6:7], v[34:37], off nt
	v_cvt_pk_bf16_f32 v3, v13, v17
	v_cvt_pk_bf16_f32 v4, v21, v25
	v_cvt_pk_bf16_f32 v5, v29, v33
	v_lshl_add_u64 v[6:7], v[6:7], 0, s[10:11]
	global_store_dwordx4 v[6:7], v[2:5], off nt

.LBB0_738:
	s_waitcnt vmcnt(14)
	v_add_u32_e32 v2, s60, v156
	v_mad_i64_i32 v[2:3], s[10:11], v2, s42, 0
	v_lshl_add_u64 v[2:3], v[2:3], 2, s[64:65]
	s_ashr_i32 s63, s62, 31
	s_ashr_i32 s43, s42, 31
	v_lshl_add_u64 v[2:3], s[62:63], 2, v[2:3]
	s_waitcnt vmcnt(1)
	v_lshlrev_b32_e32 v136, 2, v158
	v_lshl_add_u64 v[2:3], v[2:3], 0, v[136:137]
	s_lshl_b64 s[10:11], s[42:43], 2
	v_lshl_add_u64 v[6:7], v[2:3], 0, s[10:11]
	v_lshl_add_u64 v[10:11], v[6:7], 0, s[10:11]
	v_lshl_add_u64 v[14:15], v[10:11], 0, s[10:11]
	v_lshl_add_u64 v[18:19], v[14:15], 0, s[10:11]
	v_lshl_add_u64 v[22:23], v[18:19], 0, s[10:11]
	v_lshl_add_u64 v[26:27], v[22:23], 0, s[10:11]
	s_waitcnt vmcnt(0)
	v_lshl_add_u64 v[30:31], v[26:27], 0, s[10:11]
	global_load_dwordx4 v[98:101], v[2:3], off nt
	global_load_dwordx4 v[66:69], v[2:3], off offset:128 nt
	global_load_dwordx4 v[102:105], v[6:7], off nt
	global_load_dwordx4 v[70:73], v[6:7], off offset:128 nt
	global_load_dwordx4 v[106:109], v[10:11], off nt
	global_load_dwordx4 v[74:77], v[10:11], off offset:128 nt
	global_load_dwordx4 v[110:113], v[14:15], off nt
	global_load_dwordx4 v[78:81], v[14:15], off offset:128 nt
	global_load_dwordx4 v[114:117], v[18:19], off nt
	global_load_dwordx4 v[82:85], v[18:19], off offset:128 nt
	global_load_dwordx4 v[118:121], v[22:23], off nt
	global_load_dwordx4 v[86:89], v[22:23], off offset:128 nt
	global_load_dwordx4 v[122:125], v[26:27], off nt
	global_load_dwordx4 v[90:93], v[26:27], off offset:128 nt
	global_load_dwordx4 v[126:129], v[30:31], off nt
	global_load_dwordx4 v[94:97], v[30:31], off offset:128 nt
	global_load_dwordx4 v[34:37], v[2:3], off offset:256 nt
	s_nop 0
	global_load_dwordx4 v[2:5], v[2:3], off offset:384 nt
	s_nop 0
	global_load_dwordx4 v[38:41], v[6:7], off offset:256 nt
	s_nop 0
	global_load_dwordx4 v[6:9], v[6:7], off offset:384 nt
	s_nop 0
	global_load_dwordx4 v[42:45], v[10:11], off offset:256 nt
	s_nop 0
	global_load_dwordx4 v[10:13], v[10:11], off offset:384 nt
	s_nop 0
	global_load_dwordx4 v[46:49], v[14:15], off offset:256 nt
	s_nop 0
	global_load_dwordx4 v[14:17], v[14:15], off offset:384 nt
	s_nop 0
	global_load_dwordx4 v[50:53], v[18:19], off offset:256 nt
	s_nop 0
	global_load_dwordx4 v[18:21], v[18:19], off offset:384 nt
	s_nop 0
	global_load_dwordx4 v[54:57], v[22:23], off offset:256 nt
	s_nop 0
	global_load_dwordx4 v[22:25], v[22:23], off offset:384 nt
	s_nop 0
	global_load_dwordx4 v[58:61], v[26:27], off offset:256 nt
	s_nop 0
	global_load_dwordx4 v[26:29], v[26:27], off offset:384 nt
	s_nop 0
	global_load_dwordx4 v[62:65], v[30:31], off offset:256 nt
	s_nop 0
	global_load_dwordx4 v[30:33], v[30:31], off offset:384 nt
	s_cmp_lg_u32 s18, 0
	s_cselect_b64 s[10:11], -1, 0
	s_ashr_i32 s67, s66, 31
	s_ashr_i32 s61, s60, 31
	v_add_u32_e32 v130, s17, v158
	s_cmp_eq_u32 s18, 0
	v_mad_i64_i32 v[130:131], s[30:31], v130, s66, 0
	s_cbranch_scc1 .LBB0_749
	s_waitcnt vmcnt(31)
	v_mul_f32_e32 v136, 0x42000000, v98
	s_waitcnt vmcnt(29)
	v_mul_f32_e32 v165, 0x42000000, v102
	v_mov_b32_e32 v198, v137
	v_cvt_pk_fp8_f32 v198, v136, v165
	s_waitcnt vmcnt(23)
	v_mul_f32_e32 v136, 0x42000000, v114
	s_waitcnt vmcnt(21)
	v_mul_f32_e32 v165, 0x42000000, v118
	v_mov_b32_e32 v199, v137
	v_cvt_pk_fp8_f32 v199, v136, v165
	v_mul_f32_e32 v167, 0x42000000, v106
	v_mul_f32_e32 v169, 0x42000000, v110
	v_cvt_pk_fp8_f32 v198, v167, v169 op_sel:[0,0,1]
	s_waitcnt vmcnt(19)
	v_mul_f32_e32 v167, 0x42000000, v122
	s_waitcnt vmcnt(17)
	v_mul_f32_e32 v169, 0x42000000, v126
	v_cvt_pk_fp8_f32 v199, v167, v169 op_sel:[0,0,1]
	v_lshl_add_u64 v[132:133], s[86:87], 0, v[130:131]
	v_lshl_add_u64 v[132:133], v[132:133], 0, s[60:61]
	v_lshl_add_u64 v[132:133], v[132:133], 0, v[156:157]
	global_store_dwordx2 v[132:133], v[198:199], off nt
	v_mul_f32_e32 v136, 0x42000000, v99
	v_mul_f32_e32 v165, 0x42000000, v103
	v_mov_b32_e32 v198, v137
	v_cvt_pk_fp8_f32 v198, v136, v165
	v_mul_f32_e32 v136, 0x42000000, v115
	v_mul_f32_e32 v165, 0x42000000, v119
	v_mov_b32_e32 v199, v137
	v_cvt_pk_fp8_f32 v199, v136, v165
	v_mul_f32_e32 v167, 0x42000000, v107
	v_mul_f32_e32 v169, 0x42000000, v111
	v_cvt_pk_fp8_f32 v198, v167, v169 op_sel:[0,0,1]
	v_mul_f32_e32 v167, 0x42000000, v123
	v_mul_f32_e32 v169, 0x42000000, v127
	v_cvt_pk_fp8_f32 v199, v167, v169 op_sel:[0,0,1]
	v_lshl_add_u64 v[132:133], v[132:133], 0, s[66:67]
	v_mul_f32_e32 v136, 0x42000000, v100
	v_mul_f32_e32 v165, 0x42000000, v104
	global_store_dwordx2 v[132:133], v[198:199], off nt
	v_mov_b32_e32 v198, v137
	v_cvt_pk_fp8_f32 v198, v136, v165
	v_mul_f32_e32 v136, 0x42000000, v116
	v_mul_f32_e32 v165, 0x42000000, v120
	v_mov_b32_e32 v199, v137
	v_cvt_pk_fp8_f32 v199, v136, v165
	v_mul_f32_e32 v167, 0x42000000, v108
	v_mul_f32_e32 v169, 0x42000000, v112
	v_cvt_pk_fp8_f32 v198, v167, v169 op_sel:[0,0,1]
	v_mul_f32_e32 v167, 0x42000000, v124
	v_mul_f32_e32 v169, 0x42000000, v128
	v_cvt_pk_fp8_f32 v199, v167, v169 op_sel:[0,0,1]
	v_lshl_add_u64 v[132:133], v[132:133], 0, s[66:67]
	v_mul_f32_e32 v136, 0x42000000, v101
	v_mul_f32_e32 v165, 0x42000000, v105
	global_store_dwordx2 v[132:133], v[198:199], off nt
	v_mov_b32_e32 v198, v137
	v_cvt_pk_fp8_f32 v198, v136, v165
	v_mul_f32_e32 v136, 0x42000000, v117
	v_mul_f32_e32 v165, 0x42000000, v121
	v_mov_b32_e32 v199, v137
	v_cvt_pk_fp8_f32 v199, v136, v165
	v_mul_f32_e32 v167, 0x42000000, v109
	v_mul_f32_e32 v169, 0x42000000, v113
	v_cvt_pk_fp8_f32 v198, v167, v169 op_sel:[0,0,1]
	v_mul_f32_e32 v167, 0x42000000, v125
	v_mul_f32_e32 v169, 0x42000000, v129
	v_cvt_pk_fp8_f32 v199, v167, v169 op_sel:[0,0,1]
	v_lshl_add_u64 v[132:133], v[132:133], 0, s[66:67]
	global_store_dwordx2 v[132:133], v[198:199], off nt
	v_lshlrev_b32_e32 v136, 1, v156
	s_cbranch_execnz .LBB0_741
.LBB0_740:
	v_lshl_add_u64 v[130:131], v[130:131], 1, s[86:87]
	v_lshl_add_u64 v[130:131], s[60:61], 1, v[130:131]
	v_lshl_add_u64 v[198:199], v[130:131], 0, v[136:137]
	s_waitcnt vmcnt(29)
	v_cvt_pk_bf16_f32 v130, v98, v102
	s_waitcnt vmcnt(25)
	v_cvt_pk_bf16_f32 v131, v106, v110
	s_waitcnt vmcnt(21)
	v_cvt_pk_bf16_f32 v132, v114, v118
	s_waitcnt vmcnt(17)
	v_cvt_pk_bf16_f32 v133, v122, v126
	s_lshl_b64 s[30:31], s[66:67], 1
	global_store_dwordx4 v[198:199], v[130:133], off nt
	s_nop 1
	v_cvt_pk_bf16_f32 v130, v99, v103
	v_cvt_pk_bf16_f32 v131, v107, v111
	v_cvt_pk_bf16_f32 v132, v115, v119
	v_cvt_pk_bf16_f32 v133, v123, v127
	v_lshl_add_u64 v[98:99], v[198:199], 0, s[30:31]
	global_store_dwordx4 v[98:99], v[130:133], off nt
	v_lshl_add_u64 v[102:103], v[98:99], 0, s[30:31]
	v_cvt_pk_bf16_f32 v98, v101, v105
	v_cvt_pk_bf16_f32 v130, v100, v104
	v_cvt_pk_bf16_f32 v131, v108, v112
	v_cvt_pk_bf16_f32 v132, v116, v120
	v_cvt_pk_bf16_f32 v133, v124, v128
	global_store_dwordx4 v[102:103], v[130:133], off nt
	v_cvt_pk_bf16_f32 v99, v109, v113
	v_cvt_pk_bf16_f32 v100, v117, v121
	v_cvt_pk_bf16_f32 v101, v125, v129
	v_lshl_add_u64 v[102:103], v[102:103], 0, s[30:31]
	global_store_dwordx4 v[102:103], v[98:101], off nt
.LBB0_741:
	s_waitcnt vmcnt(31)
	s_nop 0
	v_add_u32_e32 v98, s17, v145
	v_cndmask_b32_e64 v99, 0, 1, s[10:11]
	v_cmp_ne_u32_e64 s[30:31], 1, v99
	s_andn2_b64 vcc, exec, s[10:11]
	v_mad_i64_i32 v[98:99], s[10:11], v98, s66, 0
	s_cbranch_vccnz .LBB0_750
	s_waitcnt vmcnt(29)
	v_mul_f32_e32 v103, 0x42000000, v66
	s_waitcnt vmcnt(28)
	v_mul_f32_e32 v104, 0x42000000, v70
	v_mov_b32_e32 v102, v137
	v_cvt_pk_fp8_f32 v102, v103, v104
	s_waitcnt vmcnt(26)
	v_mul_f32_e32 v105, 0x42000000, v74
	s_waitcnt vmcnt(24)
	v_mul_f32_e32 v106, 0x42000000, v78
	s_waitcnt vmcnt(22)
	v_mul_f32_e32 v104, 0x42000000, v82
	v_cvt_pk_fp8_f32 v102, v105, v106 op_sel:[0,0,1]
	s_waitcnt vmcnt(20)
	v_mul_f32_e32 v105, 0x42000000, v86
	v_mov_b32_e32 v103, v137
	v_cvt_pk_fp8_f32 v103, v104, v105
	s_waitcnt vmcnt(18)
	v_mul_f32_e32 v106, 0x42000000, v90
	s_waitcnt vmcnt(16)
	v_mul_f32_e32 v107, 0x42000000, v94
	v_lshl_add_u64 v[100:101], s[86:87], 0, v[98:99]
	v_cvt_pk_fp8_f32 v103, v106, v107 op_sel:[0,0,1]
	v_lshl_add_u64 v[100:101], v[100:101], 0, s[60:61]
	v_lshl_add_u64 v[100:101], v[100:101], 0, v[156:157]
	v_mul_f32_e32 v104, 0x42000000, v71
	global_store_dwordx2 v[100:101], v[102:103], off nt
	v_mul_f32_e32 v103, 0x42000000, v67
	v_mov_b32_e32 v102, v137
	v_cvt_pk_fp8_f32 v102, v103, v104
	v_mul_f32_e32 v105, 0x42000000, v75
	v_mul_f32_e32 v106, 0x42000000, v79
	v_mul_f32_e32 v104, 0x42000000, v83
	v_cvt_pk_fp8_f32 v102, v105, v106 op_sel:[0,0,1]
	v_mul_f32_e32 v105, 0x42000000, v87
	v_mov_b32_e32 v103, v137
	v_cvt_pk_fp8_f32 v103, v104, v105
	v_mul_f32_e32 v106, 0x42000000, v91
	v_mul_f32_e32 v107, 0x42000000, v95
	v_lshl_add_u64 v[100:101], v[100:101], 0, s[66:67]
	v_cvt_pk_fp8_f32 v103, v106, v107 op_sel:[0,0,1]
	v_mul_f32_e32 v104, 0x42000000, v72
	v_mul_f32_e32 v105, 0x42000000, v76
	v_mul_f32_e32 v106, 0x42000000, v80
	global_store_dwordx2 v[100:101], v[102:103], off nt
	v_mul_f32_e32 v103, 0x42000000, v68
	v_mov_b32_e32 v102, v137
	v_cvt_pk_fp8_f32 v102, v103, v104
	v_mul_f32_e32 v104, 0x42000000, v84
	v_mov_b32_e32 v103, v137
	v_mul_f32_e32 v107, 0x42000000, v96
	v_cvt_pk_fp8_f32 v102, v105, v106 op_sel:[0,0,1]
	v_mul_f32_e32 v105, 0x42000000, v88
	v_cvt_pk_fp8_f32 v103, v104, v105
	v_mul_f32_e32 v106, 0x42000000, v92
	v_lshl_add_u64 v[100:101], v[100:101], 0, s[66:67]
	v_mul_f32_e32 v104, 0x42000000, v73
	v_cvt_pk_fp8_f32 v103, v106, v107 op_sel:[0,0,1]
	v_mul_f32_e32 v105, 0x42000000, v77
	v_mul_f32_e32 v106, 0x42000000, v81
	v_mul_f32_e32 v107, 0x42000000, v97
	global_store_dwordx2 v[100:101], v[102:103], off nt
	v_mul_f32_e32 v103, 0x42000000, v69
	v_mov_b32_e32 v102, v137
	v_cvt_pk_fp8_f32 v102, v103, v104
	v_mul_f32_e32 v104, 0x42000000, v85
	v_mov_b32_e32 v103, v137
	v_lshl_add_u64 v[100:101], v[100:101], 0, s[66:67]
	v_cvt_pk_fp8_f32 v102, v105, v106 op_sel:[0,0,1]
	v_mul_f32_e32 v105, 0x42000000, v89
	v_cvt_pk_fp8_f32 v103, v104, v105
	v_mul_f32_e32 v106, 0x42000000, v93
	v_cvt_pk_fp8_f32 v103, v106, v107 op_sel:[0,0,1]
	global_store_dwordx2 v[100:101], v[102:103], off nt
	s_cbranch_execnz .LBB0_744
.LBB0_743:
	v_lshl_add_u64 v[98:99], v[98:99], 1, s[86:87]
	v_lshl_add_u64 v[98:99], s[60:61], 1, v[98:99]
	s_waitcnt vmcnt(29)
	v_lshl_add_u64 v[102:103], v[98:99], 0, v[136:137]
	s_waitcnt vmcnt(28)
	v_cvt_pk_bf16_f32 v98, v66, v70
	s_waitcnt vmcnt(24)
	v_cvt_pk_bf16_f32 v99, v74, v78
	s_waitcnt vmcnt(20)
	v_cvt_pk_bf16_f32 v100, v82, v86
	s_waitcnt vmcnt(16)
	v_cvt_pk_bf16_f32 v101, v90, v94
	s_lshl_b64 s[10:11], s[66:67], 1
	global_store_dwordx4 v[102:103], v[98:101], off nt
	s_nop 1
	v_cvt_pk_bf16_f32 v98, v67, v71
	v_cvt_pk_bf16_f32 v99, v75, v79
	v_cvt_pk_bf16_f32 v100, v83, v87
	v_cvt_pk_bf16_f32 v101, v91, v95
	v_lshl_add_u64 v[66:67], v[102:103], 0, s[10:11]
	global_store_dwordx4 v[66:67], v[98:101], off nt
	v_lshl_add_u64 v[70:71], v[66:67], 0, s[10:11]
	v_cvt_pk_bf16_f32 v66, v69, v73
	v_cvt_pk_bf16_f32 v98, v68, v72
	v_cvt_pk_bf16_f32 v99, v76, v80
	v_cvt_pk_bf16_f32 v100, v84, v88
	v_cvt_pk_bf16_f32 v101, v92, v96
	global_store_dwordx4 v[70:71], v[98:101], off nt
	v_cvt_pk_bf16_f32 v67, v77, v81
	v_cvt_pk_bf16_f32 v68, v85, v89
	v_cvt_pk_bf16_f32 v69, v93, v97
	v_lshl_add_u64 v[70:71], v[70:71], 0, s[10:11]
	global_store_dwordx4 v[70:71], v[66:69], off nt
.LBB0_744:
	s_waitcnt vmcnt(30)
	s_nop 0
	v_add_u32_e32 v66, s17, v153
	s_and_b64 vcc, exec, s[30:31]
	v_mad_i64_i32 v[66:67], s[10:11], v66, s66, 0
	s_cbranch_vccnz .LBB0_751
	s_waitcnt vmcnt(15)
	v_mul_f32_e32 v71, 0x42000000, v34
	s_waitcnt vmcnt(13)
	v_mul_f32_e32 v72, 0x42000000, v38
	v_mov_b32_e32 v70, v137
	v_cvt_pk_fp8_f32 v70, v71, v72
	s_waitcnt vmcnt(11)
	v_mul_f32_e32 v73, 0x42000000, v42
	s_waitcnt vmcnt(9)
	v_mul_f32_e32 v74, 0x42000000, v46
	s_waitcnt vmcnt(7)
	v_mul_f32_e32 v72, 0x42000000, v50
	v_cvt_pk_fp8_f32 v70, v73, v74 op_sel:[0,0,1]
	s_waitcnt vmcnt(5)
	v_mul_f32_e32 v73, 0x42000000, v54
	v_mov_b32_e32 v71, v137
	v_cvt_pk_fp8_f32 v71, v72, v73
	s_waitcnt vmcnt(3)
	v_mul_f32_e32 v74, 0x42000000, v58
	s_waitcnt vmcnt(1)
	v_mul_f32_e32 v75, 0x42000000, v62
	v_lshl_add_u64 v[68:69], s[86:87], 0, v[66:67]
	v_cvt_pk_fp8_f32 v71, v74, v75 op_sel:[0,0,1]
	v_lshl_add_u64 v[68:69], v[68:69], 0, s[60:61]
	v_lshl_add_u64 v[68:69], v[68:69], 0, v[156:157]
	v_mul_f32_e32 v72, 0x42000000, v39
	global_store_dwordx2 v[68:69], v[70:71], off nt
	v_mul_f32_e32 v71, 0x42000000, v35
	v_mov_b32_e32 v70, v137
	v_cvt_pk_fp8_f32 v70, v71, v72
	v_mul_f32_e32 v73, 0x42000000, v43
	v_mul_f32_e32 v74, 0x42000000, v47
	v_mul_f32_e32 v72, 0x42000000, v51
	v_cvt_pk_fp8_f32 v70, v73, v74 op_sel:[0,0,1]
	v_mul_f32_e32 v73, 0x42000000, v55
	v_mov_b32_e32 v71, v137
	v_cvt_pk_fp8_f32 v71, v72, v73
	v_mul_f32_e32 v74, 0x42000000, v59
	v_mul_f32_e32 v75, 0x42000000, v63
	v_lshl_add_u64 v[68:69], v[68:69], 0, s[66:67]
	v_cvt_pk_fp8_f32 v71, v74, v75 op_sel:[0,0,1]
	v_mul_f32_e32 v72, 0x42000000, v40
	v_mul_f32_e32 v73, 0x42000000, v44
	v_mul_f32_e32 v74, 0x42000000, v48
	global_store_dwordx2 v[68:69], v[70:71], off nt
	v_mul_f32_e32 v71, 0x42000000, v36
	v_mov_b32_e32 v70, v137
	v_cvt_pk_fp8_f32 v70, v71, v72
	v_mul_f32_e32 v72, 0x42000000, v52
	v_mov_b32_e32 v71, v137
	v_mul_f32_e32 v75, 0x42000000, v64
	v_cvt_pk_fp8_f32 v70, v73, v74 op_sel:[0,0,1]
	v_mul_f32_e32 v73, 0x42000000, v56
	v_cvt_pk_fp8_f32 v71, v72, v73
	v_mul_f32_e32 v74, 0x42000000, v60
	v_lshl_add_u64 v[68:69], v[68:69], 0, s[66:67]
	v_mul_f32_e32 v72, 0x42000000, v41
	v_cvt_pk_fp8_f32 v71, v74, v75 op_sel:[0,0,1]
	v_mul_f32_e32 v73, 0x42000000, v45
	v_mul_f32_e32 v74, 0x42000000, v49
	v_mul_f32_e32 v75, 0x42000000, v65
	global_store_dwordx2 v[68:69], v[70:71], off nt
	v_mul_f32_e32 v71, 0x42000000, v37
	v_mov_b32_e32 v70, v137
	v_cvt_pk_fp8_f32 v70, v71, v72
	v_mul_f32_e32 v72, 0x42000000, v53
	v_mov_b32_e32 v71, v137
	v_lshl_add_u64 v[68:69], v[68:69], 0, s[66:67]
	v_cvt_pk_fp8_f32 v70, v73, v74 op_sel:[0,0,1]
	v_mul_f32_e32 v73, 0x42000000, v57
	v_cvt_pk_fp8_f32 v71, v72, v73
	v_mul_f32_e32 v74, 0x42000000, v61
	v_cvt_pk_fp8_f32 v71, v74, v75 op_sel:[0,0,1]
	global_store_dwordx2 v[68:69], v[70:71], off nt
	s_cbranch_execnz .LBB0_747
.LBB0_746:
	v_lshl_add_u64 v[66:67], v[66:67], 1, s[86:87]
	v_lshl_add_u64 v[66:67], s[60:61], 1, v[66:67]
	s_waitcnt vmcnt(28)
	v_lshl_add_u64 v[70:71], v[66:67], 0, v[136:137]
	s_waitcnt vmcnt(13)
	v_cvt_pk_bf16_f32 v66, v34, v38
	s_waitcnt vmcnt(9)
	v_cvt_pk_bf16_f32 v67, v42, v46
	s_waitcnt vmcnt(5)
	v_cvt_pk_bf16_f32 v68, v50, v54
	s_waitcnt vmcnt(1)
	v_cvt_pk_bf16_f32 v69, v58, v62
	s_lshl_b64 s[10:11], s[66:67], 1
	global_store_dwordx4 v[70:71], v[66:69], off nt
	s_nop 1
	v_cvt_pk_bf16_f32 v66, v35, v39
	v_cvt_pk_bf16_f32 v67, v43, v47
	v_cvt_pk_bf16_f32 v68, v51, v55
	v_cvt_pk_bf16_f32 v69, v59, v63
	v_lshl_add_u64 v[34:35], v[70:71], 0, s[10:11]
	global_store_dwordx4 v[34:35], v[66:69], off nt
	v_lshl_add_u64 v[38:39], v[34:35], 0, s[10:11]
	v_cvt_pk_bf16_f32 v34, v37, v41
	v_cvt_pk_bf16_f32 v66, v36, v40
	v_cvt_pk_bf16_f32 v67, v44, v48
	v_cvt_pk_bf16_f32 v68, v52, v56
	v_cvt_pk_bf16_f32 v69, v60, v64
	global_store_dwordx4 v[38:39], v[66:69], off nt
	v_cvt_pk_bf16_f32 v35, v45, v49
	v_cvt_pk_bf16_f32 v36, v53, v57
	v_cvt_pk_bf16_f32 v37, v61, v65
	v_lshl_add_u64 v[38:39], v[38:39], 0, s[10:11]
	global_store_dwordx4 v[38:39], v[34:37], off nt
.LBB0_747:
	s_waitcnt vmcnt(15)
	s_nop 0
	v_add_u32_e32 v34, s17, v155
	s_and_b64 vcc, exec, s[30:31]
	v_mad_i64_i32 v[34:35], s[10:11], v34, s66, 0
	s_cbranch_vccnz .LBB0_752
	s_waitcnt vmcnt(13)
	v_mul_f32_e32 v39, 0x42000000, v2
	s_waitcnt vmcnt(12)
	v_mul_f32_e32 v40, 0x42000000, v6
	v_mov_b32_e32 v38, v137
	v_cvt_pk_fp8_f32 v38, v39, v40
	s_waitcnt vmcnt(10)
	v_mul_f32_e32 v41, 0x42000000, v10
	s_waitcnt vmcnt(8)
	v_mul_f32_e32 v42, 0x42000000, v14
	s_waitcnt vmcnt(6)
	v_mul_f32_e32 v40, 0x42000000, v18
	v_cvt_pk_fp8_f32 v38, v41, v42 op_sel:[0,0,1]
	s_waitcnt vmcnt(4)
	v_mul_f32_e32 v41, 0x42000000, v22
	v_mov_b32_e32 v39, v137
	v_cvt_pk_fp8_f32 v39, v40, v41
	s_waitcnt vmcnt(2)
	v_mul_f32_e32 v42, 0x42000000, v26
	s_waitcnt vmcnt(0)
	v_mul_f32_e32 v43, 0x42000000, v30
	v_lshl_add_u64 v[36:37], s[86:87], 0, v[34:35]
	v_cvt_pk_fp8_f32 v39, v42, v43 op_sel:[0,0,1]
	v_lshl_add_u64 v[36:37], v[36:37], 0, s[60:61]
	v_lshl_add_u64 v[36:37], v[36:37], 0, v[156:157]
	v_mul_f32_e32 v40, 0x42000000, v7
	global_store_dwordx2 v[36:37], v[38:39], off nt
	v_mul_f32_e32 v39, 0x42000000, v3
	v_mov_b32_e32 v38, v137
	v_cvt_pk_fp8_f32 v38, v39, v40
	v_mul_f32_e32 v41, 0x42000000, v11
	v_mul_f32_e32 v42, 0x42000000, v15
	v_mul_f32_e32 v40, 0x42000000, v19
	v_cvt_pk_fp8_f32 v38, v41, v42 op_sel:[0,0,1]
	v_mul_f32_e32 v41, 0x42000000, v23
	v_mov_b32_e32 v39, v137
	v_cvt_pk_fp8_f32 v39, v40, v41
	v_mul_f32_e32 v42, 0x42000000, v27
	v_mul_f32_e32 v43, 0x42000000, v31
	v_lshl_add_u64 v[36:37], v[36:37], 0, s[66:67]
	v_cvt_pk_fp8_f32 v39, v42, v43 op_sel:[0,0,1]
	v_mul_f32_e32 v40, 0x42000000, v8
	v_mul_f32_e32 v41, 0x42000000, v12
	v_mul_f32_e32 v42, 0x42000000, v16
	global_store_dwordx2 v[36:37], v[38:39], off nt
	v_mul_f32_e32 v39, 0x42000000, v4
	v_mov_b32_e32 v38, v137
	v_cvt_pk_fp8_f32 v38, v39, v40
	v_mul_f32_e32 v40, 0x42000000, v20
	v_mov_b32_e32 v39, v137
	v_mul_f32_e32 v43, 0x42000000, v32
	v_cvt_pk_fp8_f32 v38, v41, v42 op_sel:[0,0,1]
	v_mul_f32_e32 v41, 0x42000000, v24
	v_cvt_pk_fp8_f32 v39, v40, v41
	v_mul_f32_e32 v42, 0x42000000, v28
	v_lshl_add_u64 v[36:37], v[36:37], 0, s[66:67]
	v_mul_f32_e32 v40, 0x42000000, v9
	v_cvt_pk_fp8_f32 v39, v42, v43 op_sel:[0,0,1]
	v_mul_f32_e32 v41, 0x42000000, v13
	v_mul_f32_e32 v42, 0x42000000, v17
	v_mul_f32_e32 v43, 0x42000000, v33
	global_store_dwordx2 v[36:37], v[38:39], off nt
	v_mul_f32_e32 v39, 0x42000000, v5
	v_mov_b32_e32 v38, v137
	v_cvt_pk_fp8_f32 v38, v39, v40
	v_mul_f32_e32 v40, 0x42000000, v21
	v_mov_b32_e32 v39, v137
	v_lshl_add_u64 v[36:37], v[36:37], 0, s[66:67]
	v_cvt_pk_fp8_f32 v38, v41, v42 op_sel:[0,0,1]
	v_mul_f32_e32 v41, 0x42000000, v25
	v_cvt_pk_fp8_f32 v39, v40, v41
	v_mul_f32_e32 v42, 0x42000000, v29
	v_cvt_pk_fp8_f32 v39, v42, v43 op_sel:[0,0,1]
	global_store_dwordx2 v[36:37], v[38:39], off nt
	s_cbranch_execnz .LBB0_713
	s_branch .LBB0_712

.LBB0_757:
	v_lshl_add_u64 v[42:43], v[42:43], 1, s[20:21]
	v_lshl_add_u64 v[42:43], s[18:19], 1, v[42:43]
	v_lshlrev_b32_e32 v38, 1, v34
	v_lshl_add_u64 v[46:47], v[42:43], 0, v[38:39]
	s_waitcnt vmcnt(6)
	v_cvt_pk_bf16_f32 v42, v2, v6
	s_waitcnt vmcnt(4)
	v_cvt_pk_bf16_f32 v43, v10, v14
	s_waitcnt vmcnt(2)
	v_cvt_pk_bf16_f32 v44, v18, v22
	s_waitcnt vmcnt(0)
	v_cvt_pk_bf16_f32 v45, v26, v30
	s_lshl_b64 s[26:27], s[24:25], 1
	global_store_dwordx4 v[46:47], v[42:45], off nt
	s_nop 1
	v_cvt_pk_bf16_f32 v42, v3, v7
	v_cvt_pk_bf16_f32 v43, v11, v15
	v_cvt_pk_bf16_f32 v44, v19, v23
	v_cvt_pk_bf16_f32 v45, v27, v31
	v_lshl_add_u64 v[2:3], v[46:47], 0, s[26:27]
	global_store_dwordx4 v[2:3], v[42:45], off nt
	v_lshl_add_u64 v[6:7], v[2:3], 0, s[26:27]
	v_cvt_pk_bf16_f32 v2, v5, v9
	v_cvt_pk_bf16_f32 v42, v4, v8
	v_cvt_pk_bf16_f32 v43, v12, v16
	v_cvt_pk_bf16_f32 v44, v20, v24
	v_cvt_pk_bf16_f32 v45, v28, v32
	global_store_dwordx4 v[6:7], v[42:45], off nt
	v_cvt_pk_bf16_f32 v3, v13, v17
	v_cvt_pk_bf16_f32 v4, v21, v25
	v_cvt_pk_bf16_f32 v5, v29, v33
	v_lshl_add_u64 v[6:7], v[6:7], 0, s[26:27]
	global_store_dwordx4 v[6:7], v[2:5], off nt

.LBB0_781:
	v_add_u32_e32 v1, s18, v34
	s_waitcnt vmcnt(7)
	v_mad_i64_i32 v[2:3], s[26:27], v1, s22, 0
	v_lshl_add_u64 v[2:3], v[2:3], 2, s[14:15]
	s_ashr_i32 s17, s16, 31
	s_ashr_i32 s23, s22, 31
	v_lshl_add_u64 v[2:3], s[16:17], 2, v[2:3]
	v_lshl_add_u64 v[2:3], v[2:3], 0, v[40:41]
	s_lshl_b64 s[26:27], s[22:23], 2
	s_waitcnt vmcnt(5)
	v_lshl_add_u64 v[10:11], v[2:3], 0, s[26:27]
	global_load_dwordx4 v[2:5], v[2:3], off nt
	s_nop 0
	global_load_dwordx4 v[6:9], v[10:11], off nt
	v_lshl_add_u64 v[10:11], v[10:11], 0, s[26:27]
	s_waitcnt vmcnt(5)
	v_lshl_add_u64 v[18:19], v[10:11], 0, s[26:27]
	global_load_dwordx4 v[10:13], v[10:11], off nt
	s_nop 0
	global_load_dwordx4 v[14:17], v[18:19], off nt
	v_lshl_add_u64 v[18:19], v[18:19], 0, s[26:27]
	s_waitcnt vmcnt(5)
	v_lshl_add_u64 v[26:27], v[18:19], 0, s[26:27]
	global_load_dwordx4 v[18:21], v[18:19], off nt
	s_nop 0
	global_load_dwordx4 v[22:25], v[26:27], off nt
	v_lshl_add_u64 v[26:27], v[26:27], 0, s[26:27]
	s_waitcnt vmcnt(6)
	v_lshl_add_u64 v[30:31], v[26:27], 0, s[26:27]
	global_load_dwordx4 v[26:29], v[26:27], off nt
	s_nop 0
	global_load_dwordx4 v[30:33], v[30:31], off nt
	s_ashr_i32 s25, s24, 31
	s_ashr_i32 s19, s18, 31
	v_add_u32_e32 v1, s34, v36
	s_cmp_eq_u32 s35, 0
	v_mad_i64_i32 v[42:43], s[26:27], v1, s24, 0
	s_cbranch_scc1 .LBB0_783
	s_waitcnt vmcnt(7)
	v_mul_f32_e32 v1, 0x42000000, v2
	s_waitcnt vmcnt(6)
	v_mul_f32_e32 v37, 0x42000000, v6
	v_mov_b32_e32 v46, 0
	v_cvt_pk_fp8_f32 v46, v1, v37
	s_waitcnt vmcnt(3)
	v_mul_f32_e32 v1, 0x42000000, v18
	s_waitcnt vmcnt(2)
	v_mul_f32_e32 v37, 0x42000000, v22
	v_mov_b32_e32 v47, 0
	v_cvt_pk_fp8_f32 v47, v1, v37
	v_mul_f32_e32 v38, 0x42000000, v10
	v_mul_f32_e32 v48, 0x42000000, v14
	s_waitcnt vmcnt(1)
	v_mul_f32_e32 v1, 0x42000000, v26
	s_waitcnt vmcnt(0)
	v_mul_f32_e32 v37, 0x42000000, v30
	v_cvt_pk_fp8_f32 v46, v38, v48 op_sel:[0,0,1]
	v_cvt_pk_fp8_f32 v47, v1, v37 op_sel:[0,0,1]
	v_mul_f32_e32 v1, 0x42000000, v3
	v_mul_f32_e32 v37, 0x42000000, v7
	v_mov_b32_e32 v48, 0
	v_cvt_pk_fp8_f32 v48, v1, v37
	v_mul_f32_e32 v1, 0x42000000, v19
	v_mul_f32_e32 v37, 0x42000000, v23
	v_mov_b32_e32 v49, 0
	v_cvt_pk_fp8_f32 v49, v1, v37
	v_lshl_add_u64 v[44:45], s[20:21], 0, v[42:43]
	v_lshl_add_u64 v[44:45], v[44:45], 0, s[18:19]
	v_mul_f32_e32 v1, 0x42000000, v27
	v_mul_f32_e32 v37, 0x42000000, v31
	v_lshl_add_u64 v[44:45], v[44:45], 0, v[34:35]
	v_mul_f32_e32 v38, 0x42000000, v11
	v_mul_f32_e32 v50, 0x42000000, v15
	v_cvt_pk_fp8_f32 v49, v1, v37 op_sel:[0,0,1]
	global_store_dwordx2 v[44:45], v[46:47], off nt
	v_mul_f32_e32 v1, 0x42000000, v4
	v_mul_f32_e32 v37, 0x42000000, v8
	v_mov_b32_e32 v46, 0
	v_cvt_pk_fp8_f32 v48, v38, v50 op_sel:[0,0,1]
	v_cvt_pk_fp8_f32 v46, v1, v37
	v_mul_f32_e32 v1, 0x42000000, v20
	v_mul_f32_e32 v37, 0x42000000, v24
	v_mov_b32_e32 v47, 0
	v_cvt_pk_fp8_f32 v47, v1, v37
	v_lshl_add_u64 v[44:45], v[44:45], 0, s[24:25]
	global_store_dwordx2 v[44:45], v[48:49], off nt
	v_mul_f32_e32 v38, 0x42000000, v12
	v_mul_f32_e32 v48, 0x42000000, v16
	v_mul_f32_e32 v1, 0x42000000, v28
	v_mul_f32_e32 v37, 0x42000000, v32
	v_cvt_pk_fp8_f32 v46, v38, v48 op_sel:[0,0,1]
	v_cvt_pk_fp8_f32 v47, v1, v37 op_sel:[0,0,1]
	v_mul_f32_e32 v1, 0x42000000, v5
	v_mul_f32_e32 v37, 0x42000000, v9
	v_mov_b32_e32 v48, 0
	v_cvt_pk_fp8_f32 v48, v1, v37
	v_mul_f32_e32 v1, 0x42000000, v21
	v_mul_f32_e32 v37, 0x42000000, v25
	v_mov_b32_e32 v49, 0
	v_cvt_pk_fp8_f32 v49, v1, v37
	v_mul_f32_e32 v38, 0x42000000, v13
	v_mul_f32_e32 v50, 0x42000000, v17
	v_mul_f32_e32 v1, 0x42000000, v29
	v_mul_f32_e32 v37, 0x42000000, v33
	v_cvt_pk_fp8_f32 v48, v38, v50 op_sel:[0,0,1]
	v_cvt_pk_fp8_f32 v49, v1, v37 op_sel:[0,0,1]
	v_lshl_add_u64 v[44:45], v[44:45], 0, s[24:25]
	global_store_dwordx2 v[44:45], v[46:47], off nt
	v_lshl_add_u64 v[44:45], v[44:45], 0, s[24:25]
	global_store_dwordx2 v[44:45], v[48:49], off nt
	s_cbranch_execnz .LBB0_758
	s_branch .LBB0_757

.LBB0_934:
	v_add_u32_e32 v1, s18, v34
	s_waitcnt vmcnt(7)
	v_mad_i64_i32 v[2:3], s[26:27], v1, s22, 0
	v_lshl_add_u64 v[2:3], v[2:3], 2, s[14:15]
	s_ashr_i32 s17, s16, 31
	s_ashr_i32 s23, s22, 31
	v_lshl_add_u64 v[2:3], s[16:17], 2, v[2:3]
	v_lshl_add_u64 v[2:3], v[2:3], 0, v[40:41]
	s_lshl_b64 s[26:27], s[22:23], 2
	s_waitcnt vmcnt(5)
	v_lshl_add_u64 v[10:11], v[2:3], 0, s[26:27]
	global_load_dwordx4 v[2:5], v[2:3], off nt
	s_nop 0
	global_load_dwordx4 v[6:9], v[10:11], off nt
	v_lshl_add_u64 v[10:11], v[10:11], 0, s[26:27]
	s_waitcnt vmcnt(5)
	v_lshl_add_u64 v[18:19], v[10:11], 0, s[26:27]
	global_load_dwordx4 v[10:13], v[10:11], off nt
	s_nop 0
	global_load_dwordx4 v[14:17], v[18:19], off nt
	v_lshl_add_u64 v[18:19], v[18:19], 0, s[26:27]
	s_waitcnt vmcnt(5)
	v_lshl_add_u64 v[26:27], v[18:19], 0, s[26:27]
	global_load_dwordx4 v[18:21], v[18:19], off nt
	s_nop 0
	global_load_dwordx4 v[22:25], v[26:27], off nt
	v_lshl_add_u64 v[26:27], v[26:27], 0, s[26:27]
	s_waitcnt vmcnt(6)
	v_lshl_add_u64 v[30:31], v[26:27], 0, s[26:27]
	global_load_dwordx4 v[26:29], v[26:27], off nt
	s_nop 0
	global_load_dwordx4 v[30:33], v[30:31], off nt
	s_ashr_i32 s25, s24, 31
	s_ashr_i32 s19, s18, 31
	v_add_u32_e32 v1, s35, v36
	s_cmp_eq_u32 s42, 0
	v_mad_i64_i32 v[42:43], s[26:27], v1, s24, 0
	s_cbranch_scc1 .LBB0_936
	s_waitcnt vmcnt(7)
	v_mul_f32_e32 v1, 0x42000000, v2
	s_waitcnt vmcnt(6)
	v_mul_f32_e32 v37, 0x42000000, v6
	v_mov_b32_e32 v46, 0
	v_cvt_pk_fp8_f32 v46, v1, v37
	s_waitcnt vmcnt(3)
	v_mul_f32_e32 v1, 0x42000000, v18
	s_waitcnt vmcnt(2)
	v_mul_f32_e32 v37, 0x42000000, v22
	v_mov_b32_e32 v47, 0
	v_cvt_pk_fp8_f32 v47, v1, v37
	v_mul_f32_e32 v38, 0x42000000, v10
	v_mul_f32_e32 v48, 0x42000000, v14
	s_waitcnt vmcnt(1)
	v_mul_f32_e32 v1, 0x42000000, v26
	s_waitcnt vmcnt(0)
	v_mul_f32_e32 v37, 0x42000000, v30
	v_cvt_pk_fp8_f32 v46, v38, v48 op_sel:[0,0,1]
	v_cvt_pk_fp8_f32 v47, v1, v37 op_sel:[0,0,1]
	v_mul_f32_e32 v1, 0x42000000, v3
	v_mul_f32_e32 v37, 0x42000000, v7
	v_mov_b32_e32 v48, 0
	v_cvt_pk_fp8_f32 v48, v1, v37
	v_mul_f32_e32 v1, 0x42000000, v19
	v_mul_f32_e32 v37, 0x42000000, v23
	v_mov_b32_e32 v49, 0
	v_cvt_pk_fp8_f32 v49, v1, v37
	v_lshl_add_u64 v[44:45], s[20:21], 0, v[42:43]
	v_lshl_add_u64 v[44:45], v[44:45], 0, s[18:19]
	v_mul_f32_e32 v1, 0x42000000, v27
	v_mul_f32_e32 v37, 0x42000000, v31
	v_lshl_add_u64 v[44:45], v[44:45], 0, v[34:35]
	v_mul_f32_e32 v38, 0x42000000, v11
	v_mul_f32_e32 v50, 0x42000000, v15
	v_cvt_pk_fp8_f32 v49, v1, v37 op_sel:[0,0,1]
	global_store_dwordx2 v[44:45], v[46:47], off nt
	v_mul_f32_e32 v1, 0x42000000, v4
	v_mul_f32_e32 v37, 0x42000000, v8
	v_mov_b32_e32 v46, 0
	v_cvt_pk_fp8_f32 v48, v38, v50 op_sel:[0,0,1]
	v_cvt_pk_fp8_f32 v46, v1, v37
	v_mul_f32_e32 v1, 0x42000000, v20
	v_mul_f32_e32 v37, 0x42000000, v24
	v_mov_b32_e32 v47, 0
	v_cvt_pk_fp8_f32 v47, v1, v37
	v_lshl_add_u64 v[44:45], v[44:45], 0, s[24:25]
	global_store_dwordx2 v[44:45], v[48:49], off nt
	v_mul_f32_e32 v38, 0x42000000, v12
	v_mul_f32_e32 v48, 0x42000000, v16
	v_mul_f32_e32 v1, 0x42000000, v28
	v_mul_f32_e32 v37, 0x42000000, v32
	v_cvt_pk_fp8_f32 v46, v38, v48 op_sel:[0,0,1]
	v_cvt_pk_fp8_f32 v47, v1, v37 op_sel:[0,0,1]
	v_mul_f32_e32 v1, 0x42000000, v5
	v_mul_f32_e32 v37, 0x42000000, v9
	v_mov_b32_e32 v48, 0
	v_cvt_pk_fp8_f32 v48, v1, v37
	v_mul_f32_e32 v1, 0x42000000, v21
	v_mul_f32_e32 v37, 0x42000000, v25
	v_mov_b32_e32 v49, 0
	v_cvt_pk_fp8_f32 v49, v1, v37
	v_mul_f32_e32 v38, 0x42000000, v13
	v_mul_f32_e32 v50, 0x42000000, v17
	v_mul_f32_e32 v1, 0x42000000, v29
	v_mul_f32_e32 v37, 0x42000000, v33
	v_cvt_pk_fp8_f32 v48, v38, v50 op_sel:[0,0,1]
	v_cvt_pk_fp8_f32 v49, v1, v37 op_sel:[0,0,1]
	v_lshl_add_u64 v[44:45], v[44:45], 0, s[24:25]
	global_store_dwordx2 v[44:45], v[46:47], off nt
	v_lshl_add_u64 v[44:45], v[44:45], 0, s[24:25]
	global_store_dwordx2 v[44:45], v[48:49], off nt
	s_cbranch_execnz .LBB0_911
	s_branch .LBB0_910

.LBB0_1008:
	v_lshl_add_u64 v[34:35], v[34:35], 1, s[58:59]
	v_lshl_add_u64 v[34:35], s[42:43], 1, v[34:35]
	s_waitcnt vmcnt(14)
	v_lshl_add_u64 v[38:39], v[34:35], 0, v[70:71]
	s_waitcnt vmcnt(6)
	v_cvt_pk_bf16_f32 v34, v2, v6
	s_waitcnt vmcnt(4)
	v_cvt_pk_bf16_f32 v35, v10, v14
	s_waitcnt vmcnt(2)
	v_cvt_pk_bf16_f32 v36, v18, v22
	s_waitcnt vmcnt(0)
	v_cvt_pk_bf16_f32 v37, v26, v30
	s_lshl_b64 s[60:61], s[52:53], 1
	global_store_dwordx4 v[38:39], v[34:37], off nt
	s_nop 1
	v_cvt_pk_bf16_f32 v34, v3, v7
	v_cvt_pk_bf16_f32 v35, v11, v15
	v_cvt_pk_bf16_f32 v36, v19, v23
	v_cvt_pk_bf16_f32 v37, v27, v31
	v_lshl_add_u64 v[2:3], v[38:39], 0, s[60:61]
	global_store_dwordx4 v[2:3], v[34:37], off nt
	v_lshl_add_u64 v[6:7], v[2:3], 0, s[60:61]
	v_cvt_pk_bf16_f32 v2, v5, v9
	v_cvt_pk_bf16_f32 v34, v4, v8
	v_cvt_pk_bf16_f32 v35, v12, v16
	v_cvt_pk_bf16_f32 v36, v20, v24
	v_cvt_pk_bf16_f32 v37, v28, v32
	global_store_dwordx4 v[6:7], v[34:37], off nt
	v_cvt_pk_bf16_f32 v3, v13, v17
	v_cvt_pk_bf16_f32 v4, v21, v25
	v_cvt_pk_bf16_f32 v5, v29, v33
	v_lshl_add_u64 v[6:7], v[6:7], 0, s[60:61]
	global_store_dwordx4 v[6:7], v[2:5], off nt

.LBB0_1054:
	v_add_u32_e32 v1, s30, v66
	s_waitcnt vmcnt(7)
	v_mad_i64_i32 v[2:3], s[60:61], v1, s48, 0
	v_lshl_add_u64 v[2:3], v[2:3], 2, s[34:35]
	s_ashr_i32 s27, s26, 31
	s_ashr_i32 s49, s48, 31
	v_lshl_add_u64 v[2:3], s[26:27], 2, v[2:3]
	v_lshl_add_u64 v[2:3], v[2:3], 0, v[72:73]
	s_lshl_b64 s[60:61], s[48:49], 2
	v_lshl_add_u64 v[4:5], v[2:3], 0, s[60:61]
	global_load_dwordx4 v[34:37], v[2:3], off nt
	global_load_dwordx4 v[38:41], v[4:5], off nt
	v_lshl_add_u64 v[2:3], v[4:5], 0, s[60:61]
	v_lshl_add_u64 v[4:5], v[2:3], 0, s[60:61]
	global_load_dwordx4 v[42:45], v[2:3], off nt
	global_load_dwordx4 v[46:49], v[4:5], off nt
	v_lshl_add_u64 v[2:3], v[4:5], 0, s[60:61]
	v_lshl_add_u64 v[4:5], v[2:3], 0, s[60:61]
	global_load_dwordx4 v[50:53], v[2:3], off nt
	global_load_dwordx4 v[54:57], v[4:5], off nt
	v_lshl_add_u64 v[2:3], v[4:5], 0, s[60:61]
	v_add_u32_e32 v1, s42, v66
	v_lshl_add_u64 v[4:5], v[2:3], 0, s[60:61]
	global_load_dwordx4 v[58:61], v[2:3], off nt
	global_load_dwordx4 v[62:65], v[4:5], off nt
	v_mad_i64_i32 v[2:3], s[60:61], v1, s54, 0
	v_lshl_add_u64 v[2:3], v[2:3], 2, s[44:45]
	s_ashr_i32 s29, s28, 31
	s_ashr_i32 s55, s54, 31
	v_lshl_add_u64 v[2:3], s[28:29], 2, v[2:3]
	v_lshl_add_u64 v[2:3], v[2:3], 0, v[72:73]
	s_lshl_b64 s[60:61], s[54:55], 2
	s_waitcnt vmcnt(13)
	v_lshl_add_u64 v[10:11], v[2:3], 0, s[60:61]
	global_load_dwordx4 v[2:5], v[2:3], off nt
	s_nop 0
	global_load_dwordx4 v[6:9], v[10:11], off nt
	v_lshl_add_u64 v[10:11], v[10:11], 0, s[60:61]
	s_waitcnt vmcnt(13)
	v_lshl_add_u64 v[18:19], v[10:11], 0, s[60:61]
	global_load_dwordx4 v[10:13], v[10:11], off nt
	s_nop 0
	global_load_dwordx4 v[14:17], v[18:19], off nt
	v_lshl_add_u64 v[18:19], v[18:19], 0, s[60:61]
	s_waitcnt vmcnt(13)
	v_lshl_add_u64 v[26:27], v[18:19], 0, s[60:61]
	global_load_dwordx4 v[18:21], v[18:19], off nt
	s_nop 0
	global_load_dwordx4 v[22:25], v[26:27], off nt
	v_lshl_add_u64 v[26:27], v[26:27], 0, s[60:61]
	s_waitcnt vmcnt(14)
	v_lshl_add_u64 v[30:31], v[26:27], 0, s[60:61]
	global_load_dwordx4 v[26:29], v[26:27], off nt
	s_nop 0
	global_load_dwordx4 v[30:33], v[30:31], off nt
	s_ashr_i32 s47, s46, 31
	s_ashr_i32 s31, s30, 31
	v_add_u32_e32 v1, s65, v68
	s_cmp_eq_u32 s67, 0
	v_mad_i64_i32 v[74:75], s[60:61], v1, s46, 0
	s_cbranch_scc1 .LBB0_1059
	s_waitcnt vmcnt(15)
	v_mul_f32_e32 v1, 0x42000000, v34
	s_waitcnt vmcnt(14)
	v_mul_f32_e32 v69, 0x42000000, v38
	v_mov_b32_e32 v78, 0
	v_cvt_pk_fp8_f32 v78, v1, v69
	s_waitcnt vmcnt(11)
	v_mul_f32_e32 v1, 0x42000000, v50
	s_waitcnt vmcnt(10)
	v_mul_f32_e32 v69, 0x42000000, v54
	v_mov_b32_e32 v79, 0
	v_cvt_pk_fp8_f32 v79, v1, v69
	v_mul_f32_e32 v70, 0x42000000, v42
	v_mul_f32_e32 v80, 0x42000000, v46
	s_waitcnt vmcnt(9)
	v_mul_f32_e32 v1, 0x42000000, v58
	s_waitcnt vmcnt(8)
	v_mul_f32_e32 v69, 0x42000000, v62
	v_cvt_pk_fp8_f32 v78, v70, v80 op_sel:[0,0,1]
	v_cvt_pk_fp8_f32 v79, v1, v69 op_sel:[0,0,1]
	v_mul_f32_e32 v1, 0x42000000, v35
	v_mul_f32_e32 v69, 0x42000000, v39
	v_mov_b32_e32 v80, 0
	v_cvt_pk_fp8_f32 v80, v1, v69
	v_mul_f32_e32 v1, 0x42000000, v51
	v_mul_f32_e32 v69, 0x42000000, v55
	v_mov_b32_e32 v81, 0
	v_cvt_pk_fp8_f32 v81, v1, v69
	v_lshl_add_u64 v[76:77], s[56:57], 0, v[74:75]
	v_lshl_add_u64 v[76:77], v[76:77], 0, s[30:31]
	v_mul_f32_e32 v1, 0x42000000, v59
	v_mul_f32_e32 v69, 0x42000000, v63
	v_lshl_add_u64 v[76:77], v[76:77], 0, v[66:67]
	v_mul_f32_e32 v70, 0x42000000, v43
	v_mul_f32_e32 v82, 0x42000000, v47
	v_cvt_pk_fp8_f32 v81, v1, v69 op_sel:[0,0,1]
	global_store_dwordx2 v[76:77], v[78:79], off nt
	v_mul_f32_e32 v1, 0x42000000, v36
	v_mul_f32_e32 v69, 0x42000000, v40
	v_mov_b32_e32 v78, 0
	v_cvt_pk_fp8_f32 v80, v70, v82 op_sel:[0,0,1]
	v_cvt_pk_fp8_f32 v78, v1, v69
	v_mul_f32_e32 v1, 0x42000000, v52
	v_mul_f32_e32 v69, 0x42000000, v56
	v_mov_b32_e32 v79, 0
	v_cvt_pk_fp8_f32 v79, v1, v69
	v_lshl_add_u64 v[76:77], v[76:77], 0, s[46:47]
	global_store_dwordx2 v[76:77], v[80:81], off nt
	v_mul_f32_e32 v70, 0x42000000, v44
	v_mul_f32_e32 v80, 0x42000000, v48
	v_mul_f32_e32 v1, 0x42000000, v60
	v_mul_f32_e32 v69, 0x42000000, v64
	v_cvt_pk_fp8_f32 v78, v70, v80 op_sel:[0,0,1]
	v_cvt_pk_fp8_f32 v79, v1, v69 op_sel:[0,0,1]
	v_mul_f32_e32 v1, 0x42000000, v37
	v_mul_f32_e32 v69, 0x42000000, v41
	v_mov_b32_e32 v80, 0
	v_cvt_pk_fp8_f32 v80, v1, v69
	v_mul_f32_e32 v1, 0x42000000, v53
	v_mul_f32_e32 v69, 0x42000000, v57
	v_mov_b32_e32 v81, 0
	v_cvt_pk_fp8_f32 v81, v1, v69
	v_mul_f32_e32 v70, 0x42000000, v45
	v_mul_f32_e32 v82, 0x42000000, v49
	v_mul_f32_e32 v1, 0x42000000, v61
	v_mul_f32_e32 v69, 0x42000000, v65
	v_cvt_pk_fp8_f32 v80, v70, v82 op_sel:[0,0,1]
	v_cvt_pk_fp8_f32 v81, v1, v69 op_sel:[0,0,1]
	v_lshl_add_u64 v[76:77], v[76:77], 0, s[46:47]
	global_store_dwordx2 v[76:77], v[78:79], off nt
	v_lshl_add_u64 v[76:77], v[76:77], 0, s[46:47]
	global_store_dwordx2 v[76:77], v[80:81], off nt
	v_lshlrev_b32_e32 v70, 1, v66
	s_cbranch_execnz .LBB0_1057
.LBB0_1056:
	v_lshl_add_u64 v[74:75], v[74:75], 1, s[56:57]
	v_lshl_add_u64 v[74:75], s[30:31], 1, v[74:75]
	v_lshl_add_u64 v[78:79], v[74:75], 0, v[70:71]
	s_waitcnt vmcnt(14)
	v_cvt_pk_bf16_f32 v74, v34, v38
	s_waitcnt vmcnt(12)
	v_cvt_pk_bf16_f32 v75, v42, v46
	s_waitcnt vmcnt(10)
	v_cvt_pk_bf16_f32 v76, v50, v54
	s_waitcnt vmcnt(8)
	v_cvt_pk_bf16_f32 v77, v58, v62
	s_lshl_b64 s[60:61], s[46:47], 1
	global_store_dwordx4 v[78:79], v[74:77], off nt
	s_nop 1
	v_cvt_pk_bf16_f32 v74, v35, v39
	v_cvt_pk_bf16_f32 v75, v43, v47
	v_cvt_pk_bf16_f32 v76, v51, v55
	v_cvt_pk_bf16_f32 v77, v59, v63
	v_lshl_add_u64 v[34:35], v[78:79], 0, s[60:61]
	global_store_dwordx4 v[34:35], v[74:77], off nt
	v_lshl_add_u64 v[38:39], v[34:35], 0, s[60:61]
	v_cvt_pk_bf16_f32 v34, v37, v41
	v_cvt_pk_bf16_f32 v74, v36, v40
	v_cvt_pk_bf16_f32 v75, v44, v48
	v_cvt_pk_bf16_f32 v76, v52, v56
	v_cvt_pk_bf16_f32 v77, v60, v64
	global_store_dwordx4 v[38:39], v[74:77], off nt
	v_cvt_pk_bf16_f32 v35, v45, v49
	v_cvt_pk_bf16_f32 v36, v53, v57
	v_cvt_pk_bf16_f32 v37, v61, v65
	v_lshl_add_u64 v[38:39], v[38:39], 0, s[60:61]
	global_store_dwordx4 v[38:39], v[34:37], off nt
.LBB0_1057:
	s_ashr_i32 s53, s52, 31
	s_ashr_i32 s43, s42, 31
	v_add_u32_e32 v1, s66, v68
	s_cmp_eq_u32 s72, 0
	s_waitcnt vmcnt(15)
	v_mad_i64_i32 v[34:35], s[60:61], v1, s52, 0
	s_cbranch_scc1 .LBB0_1060
	s_waitcnt vmcnt(7)
	v_mul_f32_e32 v1, 0x42000000, v2
	s_waitcnt vmcnt(6)
	v_mul_f32_e32 v39, 0x42000000, v6
	v_mov_b32_e32 v38, v71
	v_cvt_pk_fp8_f32 v38, v1, v39
	s_waitcnt vmcnt(3)
	v_mul_f32_e32 v1, 0x42000000, v18
	s_waitcnt vmcnt(2)
	v_mul_f32_e32 v42, 0x42000000, v22
	v_mov_b32_e32 v39, v71
	v_cvt_pk_fp8_f32 v39, v1, v42
	v_mul_f32_e32 v40, 0x42000000, v10
	v_mul_f32_e32 v41, 0x42000000, v14
	v_cvt_pk_fp8_f32 v38, v40, v41 op_sel:[0,0,1]
	s_waitcnt vmcnt(1)
	v_mul_f32_e32 v1, 0x42000000, v26
	s_waitcnt vmcnt(0)
	v_mul_f32_e32 v40, 0x42000000, v30
	v_cvt_pk_fp8_f32 v39, v1, v40 op_sel:[0,0,1]
	v_mul_f32_e32 v1, 0x42000000, v3
	v_mul_f32_e32 v41, 0x42000000, v7
	v_mov_b32_e32 v40, v71
	v_cvt_pk_fp8_f32 v40, v1, v41
	v_mul_f32_e32 v1, 0x42000000, v19
	v_mul_f32_e32 v44, 0x42000000, v23
	v_mov_b32_e32 v41, v71
	v_cvt_pk_fp8_f32 v41, v1, v44
	v_lshl_add_u64 v[36:37], s[58:59], 0, v[34:35]
	v_lshl_add_u64 v[36:37], v[36:37], 0, s[42:43]
	v_mul_f32_e32 v42, 0x42000000, v11
	v_mul_f32_e32 v43, 0x42000000, v15
	v_cvt_pk_fp8_f32 v40, v42, v43 op_sel:[0,0,1]
	v_mul_f32_e32 v1, 0x42000000, v27
	v_mul_f32_e32 v42, 0x42000000, v31
	v_lshl_add_u64 v[36:37], v[36:37], 0, v[66:67]
	v_cvt_pk_fp8_f32 v41, v1, v42 op_sel:[0,0,1]
	global_store_dwordx2 v[36:37], v[38:39], off nt
	v_mul_f32_e32 v1, 0x42000000, v4
	v_mul_f32_e32 v39, 0x42000000, v8
	v_mov_b32_e32 v38, v71
	v_cvt_pk_fp8_f32 v38, v1, v39
	v_mul_f32_e32 v1, 0x42000000, v20
	v_mul_f32_e32 v42, 0x42000000, v24
	v_mov_b32_e32 v39, v71
	v_cvt_pk_fp8_f32 v39, v1, v42
	v_lshl_add_u64 v[36:37], v[36:37], 0, s[52:53]
	global_store_dwordx2 v[36:37], v[40:41], off nt
	v_mul_f32_e32 v40, 0x42000000, v12
	v_mul_f32_e32 v41, 0x42000000, v16
	v_cvt_pk_fp8_f32 v38, v40, v41 op_sel:[0,0,1]
	v_mul_f32_e32 v1, 0x42000000, v28
	v_mul_f32_e32 v40, 0x42000000, v32
	v_cvt_pk_fp8_f32 v39, v1, v40 op_sel:[0,0,1]
	v_mul_f32_e32 v1, 0x42000000, v5
	v_mul_f32_e32 v41, 0x42000000, v9
	v_mov_b32_e32 v40, v71
	v_cvt_pk_fp8_f32 v40, v1, v41
	v_mul_f32_e32 v1, 0x42000000, v21
	v_mul_f32_e32 v44, 0x42000000, v25
	v_mov_b32_e32 v41, v71
	v_cvt_pk_fp8_f32 v41, v1, v44
	v_mul_f32_e32 v42, 0x42000000, v13
	v_mul_f32_e32 v43, 0x42000000, v17
	v_cvt_pk_fp8_f32 v40, v42, v43 op_sel:[0,0,1]
	v_mul_f32_e32 v1, 0x42000000, v29
	v_mul_f32_e32 v42, 0x42000000, v33
	v_cvt_pk_fp8_f32 v41, v1, v42 op_sel:[0,0,1]
	v_lshl_add_u64 v[36:37], v[36:37], 0, s[52:53]
	global_store_dwordx2 v[36:37], v[38:39], off nt
	v_lshl_add_u64 v[36:37], v[36:37], 0, s[52:53]
	global_store_dwordx2 v[36:37], v[40:41], off nt
	s_cbranch_execnz .LBB0_1009
	s_branch .LBB0_1008
